# mixer phase order split by blockIdx bit 6 (groups of eight ranks)
# baseline (speedup 1.0000x reference)
; #define LAS __attribute__((address_space(3)))
; #define LAUNDER() int tp = TID0(); const int tid = tp, lane = tp & 63, wave = __builtin_amdgcn_readfirstlane(tp >> 6); (void)tid; (void)lane; (void)wave
; __global__ void __launch_bounds__(512) fwd_kernel(Args a) {
;     ...
;         if (IN(pb + 2)) {
;             if (EN_B) { LAUNDER(); LAS char* vt = (LAS char*)lds + wave * 16384;
;                 (void)vt; for (int u = blockIdx.x; u < 256; u += G) { mixerB2_unit(u, l, PROJ, YC, a.in[6] + l * 128, a.in[7] + l * 64, KMAX + l * 1024, (LAS char*)lds, tid, wave, lane); } __syncthreads(); }
;             if (EN_S1) { LAUNDER(); __syncthreads();
;                 for (int u = blockIdx.x; u < 256; u += G) ssd_part1_unit(u, PROJ, DT, H, WDT + l * 16384, a.in[11] + l * 8, a.in[8] + l * 5 * 768, a.in[9] + l * 768, a.in[10] + l * 8, STATES, TOT, lds, tid, wave, lane);
;                 __syncthreads(); }
;             if (EN_A) { LAUNDER(); LAS char* vt = (LAS char*)lds + wave * 16384;
;                 for (int u = blockIdx.x; u < 512; u += G) { mixerA1_unit(u, PROJ, YC, LPA, KMAX + l * 1024, vt, wave, lane); } }
;             if (EN_D) { LAUNDER(); LAS char* vt = (LAS char*)lds + wave * 16384;
;                 int hcur = -1; float rmax = 0.f;
;                 for (int u = blockIdx.x; u < 512; u += G) { const int hd = (u >> 4) & 3; if (hd != hcur) { rmax = d_stage_rpb(a.in[14] + l * 4 * 15 * 31, hd, vt, lane); hcur = hd; }
;                     mixerD2_unit(u, PROJ, YC, rmax, KMAX + l * 1024, vt, wave, lane); } }
;         }
.Lmx_b:
	s_cmp_eq_u32 s101, 0
	s_cbranch_scc0 .Lmx_b_go
	s_bitcmp1_b32 s66, 6
	s_cbranch_scc0 .Lmx_b_go
	s_mov_b32 s101, 1
	v_readlane_b32 s0, v253, 56
	v_readlane_b32 s1, v253, 57
	s_nop 1
	v_cndmask_b32_e64 v6, 0, 1, s[0:1]
	s_nop 0
	v_cmp_ne_u32_e64 s[36:37], 1, v6
	s_branch .LBB0_262
